# stagger 17-unit CUs in FFN-up and 5-tile CUs in in-proj (store bursts spread), hyena prompt filter copies 16 banks apart, in-proj epilogue ss prefetch
# speedup vs baseline: 1.0104x; 1.0104x over previous
.LBB0_270:
	s_mov_b64 s[4:5], s[66:67]
	s_mov_b32 s0, s85
	s_cmpk_lt_i32 s0, 64
	s_cbranch_scc1 .Lstag1_done
	s_sub_i32 s98, s0, 64
	s_mul_i32 s98, s98, 4
.Lstag1_loop:
	s_sleep 1
	s_sub_i32 s98, s98, 1
	s_cmp_gt_i32 s98, 0
	s_cbranch_scc1 .Lstag1_loop
.Lstag1_done:
	s_mov_b32 s1, s64
	v_mov_b32_e32 v8, v167
	s_cmpk_lt_i32 s0, 0x540
	s_nop 0
	v_readfirstlane_b32 s15, v8
	s_cbranch_scc0 .LBB0_286
	v_lshlrev_b32_e32 v0, 4, v8
	s_waitcnt lgkmcnt(0)
	v_add_u32_e32 v1, 0x2000, v0
	v_ashrrev_i32_e32 v2, 31, v1
	v_lshrrev_b32_e32 v2, 22, v2
	v_add_u32_e32 v2, v1, v2
	v_ashrrev_i32_e32 v9, 10, v2
	v_mul_i32_i24_e32 v2, 0x400, v9
	v_sub_u32_e32 v1, v1, v2
	s_load_dwordx2 s[4:5], s[4:5], 0xd8
	v_lshrrev_b32_e32 v2, 4, v1
	v_bitop3_b32 v1, v2, v1, 32 bitop3:0x6c
	v_ashrrev_i32_e32 v2, 31, v1
	v_lshrrev_b32_e32 v2, 26, v2
	v_add_u32_e32 v2, v1, v2
	v_lshlrev_b32_e32 v3, 3, v9
	v_readlane_b32 s6, v242, 12
	s_waitcnt lgkmcnt(0)
	s_add_u32 s2, s4, 0x2c00000
	v_ashrrev_i32_e32 v10, 6, v2
	v_and_b32_e32 v3, -16, v3
	s_mul_i32 s6, s6, 0x380000
	s_addc_u32 s20, s5, 0
	v_add_u32_e32 v3, v10, v3
	s_add_u32 s21, s4, s6
	v_and_b32_e32 v4, 3, v10
	s_mov_b32 s6, 0x1fffe0
	v_lshrrev_b32_e32 v5, 2, v3
	v_lshlrev_b32_e32 v6, 1, v3
	v_and_b32_e32 v2, 0xc0, v2
	v_and_or_b32 v4, v3, s6, v4
	v_and_b32_e32 v5, 4, v5
	v_and_b32_e32 v6, 24, v6
	v_sub_u32_e32 v1, v1, v2
	v_or3_b32 v4, v4, v5, v6
	v_lshlrev_b32_e32 v5, 5, v9
	v_ashrrev_i16_sdwa v1, v216, sext(v1) dst_sel:DWORD dst_unused:UNUSED_PAD src0_sel:DWORD src1_sel:BYTE_0
	v_and_b32_e32 v5, 32, v5
	v_bfe_i32 v11, v1, 0, 16
	v_add_lshl_u32 v1, v5, v11, 1
	v_lshl_add_u32 v128, v4, 11, v1
	v_lshl_add_u32 v130, v3, 11, v1
	v_bfe_i32 v1, v8, 27, 1
	v_lshrrev_b32_e32 v1, 22, v1
	v_add_u32_e32 v1, v0, v1
	v_and_b32_e32 v1, 0xfffffc00, v1
	v_sub_u32_e32 v0, v0, v1
	v_lshrrev_b32_e32 v1, 4, v0
	v_bitop3_b32 v1, v1, v0, 32 bitop3:0x6c
	v_ashrrev_i32_e32 v0, 31, v0
	v_lshrrev_b32_e32 v0, 26, v0
	v_add_u32_e32 v0, v1, v0
	v_ashrrev_i32_e32 v12, 6, v0
	v_ashrrev_i32_e32 v0, 31, v8
	v_lshrrev_b32_e32 v0, 26, v0
	v_add_u32_e32 v0, v8, v0
	v_ashrrev_i32_e32 v13, 6, v0
	v_lshlrev_b32_e32 v0, 3, v13
	v_and_b32_e32 v0, -16, v0
	s_addc_u32 s30, s5, 0
	s_ashr_i32 s31, s0, 31
	v_add_u32_e32 v0, v12, v0
	v_and_b32_e32 v2, 3, v12
	v_and_or_b32 v2, v0, s6, v2
	s_lshr_b32 s6, s31, 29
	v_readlane_b32 s7, v242, 13
	s_add_i32 s6, s0, s6
	s_ashr_i32 s17, s15, 6
	s_ashr_i32 s7, s6, 3
	s_and_b32 s6, s6, -8
	s_ashr_i32 s16, s15, 8
	s_lshl_b32 s34, s17, 10
	s_sub_i32 s6, s0, s6
	s_cmp_lt_i32 s6, 0
	s_cselect_b32 s8, s75, 0xa8
	s_mul_i32 s6, s6, s8
	s_add_i32 s6, s6, s7
	s_mul_hi_i32 s7, s6, 0x92492493
	s_add_i32 s7, s7, s6
	s_lshr_b32 s8, s7, 31
	s_ashr_i32 s7, s7, 5
	s_add_i32 s7, s7, s8
	s_lshl_b32 s8, s7, 3
	s_mul_i32 s7, s7, 56
	s_sub_i32 s6, s6, s7
	s_bfe_i32 s7, s6, 0x80000
	s_bfe_u32 s7, s7, 0x3000c
	s_add_i32 s7, s6, s7
	s_bfe_i32 s9, s7, 0x80000
	s_and_b32 s7, s7, 0xf8
	s_sub_i32 s6, s6, s7
	v_lshrrev_b32_e32 v3, 2, v0
	v_lshlrev_b32_e32 v4, 1, v0
	s_sext_i32_i8 s6, s6
	v_and_b32_e32 v3, 4, v3
	v_and_b32_e32 v4, 24, v4
	s_sext_i32_i16 s9, s9
	s_add_i32 s47, s8, s6
	v_or3_b32 v2, v2, v3, v4
	v_mul_i32_i24_e32 v4, 64, v12
	s_lshr_b32 s14, s9, 3
	s_lshl_b32 s6, s47, 8
	v_sub_u32_e32 v1, v1, v4
	s_ashr_i32 s7, s6, 31
	s_bfe_i64 s[8:9], s[14:15], 0x100000
	v_lshlrev_b32_e32 v3, 5, v13
	v_ashrrev_i16_sdwa v1, v216, sext(v1) dst_sel:DWORD dst_unused:UNUSED_PAD src0_sel:DWORD src1_sel:BYTE_0
	s_lshl_b64 s[6:7], s[6:7], 11
	s_lshl_b64 s[8:9], s[8:9], 19
	v_and_b32_e32 v3, 32, v3
	v_bfe_i32 v14, v1, 0, 16
	s_add_u32 s26, s21, s8
	v_add_lshl_u32 v1, v3, v14, 1
	s_addc_u32 s27, s30, s9
	s_add_i32 s35, s34, 0
	v_lshl_add_u32 v160, v2, 11, v1
	s_add_i32 m0, s35, 0x10000
	v_lshl_add_u32 v132, v0, 11, v1
	global_load_lds_dwordx4 v160, s[26:27]
	s_add_i32 m0, s35, 0x12000
	s_add_u32 s8, s26, 0x40000
	global_load_lds_dwordx4 v128, s[26:27]
	s_addc_u32 s9, s27, 0
	s_add_i32 m0, s35, 0x14000
	v_mov_b32_e32 v129, v161
	global_load_lds_dwordx4 v160, s[8:9]
	s_add_i32 m0, s35, 0x16000
	s_add_u32 s6, s2, s6
	s_addc_u32 s7, s20, s7
	s_add_i32 s36, s35, 0x2000
	global_load_lds_dwordx4 v128, s[8:9]
	s_mov_b32 m0, s35
	s_add_u32 s8, s6, 0x40000
	global_load_lds_dwordx4 v132, s[6:7]
	s_mov_b32 m0, s36
	s_addc_u32 s9, s7, 0
	s_add_i32 s37, s35, 0x4000
	global_load_lds_dwordx4 v130, s[6:7]
	s_mov_b32 m0, s37
	s_add_i32 s40, s35, 0x6000
	global_load_lds_dwordx4 v132, s[8:9]
	s_mov_b32 m0, s40
	v_mov_b32_e32 v133, v161
	global_load_lds_dwordx4 v130, s[8:9]
	v_mov_b32_e32 v131, v161
	s_cmp_eq_u32 s16, 1
	v_lshl_add_u64 v[6:7], s[26:27], 0, v[160:161]
	v_lshl_add_u64 v[4:5], s[26:27], 0, v[128:129]
	v_lshl_add_u64 v[0:1], s[6:7], 0, v[132:133]
	s_cselect_b64 s[8:9], -1, 0
	s_cmp_lg_u32 s16, 1
	v_lshl_add_u64 v[2:3], s[6:7], 0, v[130:131]
	s_cbranch_scc1 .LBB0_273
	s_barrier

.LBB0_278:
	s_ashr_i32 s19, s18, 31
	s_lshl_b64 s[22:23], s[18:19], 11
	s_add_u32 s22, s2, s22
	s_addc_u32 s23, s20, s23
	s_and_b64 s[24:25], s[4:5], exec
	s_cselect_b32 s19, s23, s7
	s_cselect_b32 s49, s22, s6
	s_ashr_i32 s17, s16, 31
	s_lshl_b64 s[24:25], s[16:17], 19
	s_add_u32 s24, s21, s24
	s_addc_u32 s25, s30, s25
	s_and_b64 s[28:29], s[4:5], exec
	s_cselect_b32 s17, s25, s27
	s_cselect_b32 s50, s24, s26
	s_add_u32 s6, s6, 0x40080
	s_addc_u32 s7, s7, 0
	s_add_u32 s51, s26, 0x100
	v_mov_b32_e32 v0, 0
	s_addc_u32 s52, s27, 0
	s_mov_b32 s53, -2
	v_mov_b32_e32 v1, v0
	v_mov_b32_e32 v2, v0
	v_mov_b32_e32 v3, v0
	v_mov_b32_e32 v4, v0
	v_mov_b32_e32 v5, v0
	v_mov_b32_e32 v6, v0
	v_mov_b32_e32 v7, v0
	v_mov_b32_e32 v16, v0
	v_mov_b32_e32 v17, v0
	v_mov_b32_e32 v18, v0
	v_mov_b32_e32 v19, v0
	v_mov_b32_e32 v20, v0
	v_mov_b32_e32 v21, v0
	v_mov_b32_e32 v22, v0
	v_mov_b32_e32 v23, v0
	v_mov_b32_e32 v32, v0
	v_mov_b32_e32 v33, v0
	v_mov_b32_e32 v34, v0
	v_mov_b32_e32 v35, v0
	v_mov_b32_e32 v36, v0
	v_mov_b32_e32 v37, v0
	v_mov_b32_e32 v38, v0
	v_mov_b32_e32 v39, v0
	v_mov_b32_e32 v48, v0
	v_mov_b32_e32 v49, v0
	v_mov_b32_e32 v50, v0
	v_mov_b32_e32 v51, v0
	v_mov_b32_e32 v52, v0
	v_mov_b32_e32 v53, v0
	v_mov_b32_e32 v54, v0
	v_mov_b32_e32 v55, v0
	v_mov_b32_e32 v8, v0
	v_mov_b32_e32 v9, v0
	v_mov_b32_e32 v10, v0
	v_mov_b32_e32 v11, v0
	v_mov_b32_e32 v12, v0
	v_mov_b32_e32 v13, v0
	v_mov_b32_e32 v14, v0
	v_mov_b32_e32 v15, v0
	v_mov_b32_e32 v24, v0
	v_mov_b32_e32 v25, v0
	v_mov_b32_e32 v26, v0
	v_mov_b32_e32 v27, v0
	v_mov_b32_e32 v28, v0
	v_mov_b32_e32 v29, v0
	v_mov_b32_e32 v30, v0
	v_mov_b32_e32 v31, v0
	v_mov_b32_e32 v40, v0
	v_mov_b32_e32 v41, v0
	v_mov_b32_e32 v42, v0
	v_mov_b32_e32 v43, v0
	v_mov_b32_e32 v44, v0
	v_mov_b32_e32 v45, v0
	v_mov_b32_e32 v46, v0
	v_mov_b32_e32 v47, v0
	v_mov_b32_e32 v56, v0
	v_mov_b32_e32 v57, v0
	v_mov_b32_e32 v58, v0
	v_mov_b32_e32 v59, v0
	v_mov_b32_e32 v60, v0
	v_mov_b32_e32 v61, v0
	v_mov_b32_e32 v62, v0
	v_mov_b32_e32 v63, v0
	v_mov_b32_e32 v64, v0
	v_mov_b32_e32 v65, v0
	v_mov_b32_e32 v66, v0
	v_mov_b32_e32 v67, v0
	v_mov_b32_e32 v68, v0
	v_mov_b32_e32 v69, v0
	v_mov_b32_e32 v70, v0
	v_mov_b32_e32 v71, v0
	v_mov_b32_e32 v80, v0
	v_mov_b32_e32 v81, v0
	v_mov_b32_e32 v82, v0
	v_mov_b32_e32 v83, v0
	v_mov_b32_e32 v84, v0
	v_mov_b32_e32 v85, v0
	v_mov_b32_e32 v86, v0
	v_mov_b32_e32 v87, v0
	v_mov_b32_e32 v96, v0
	v_mov_b32_e32 v97, v0
	v_mov_b32_e32 v98, v0
	v_mov_b32_e32 v99, v0
	v_mov_b32_e32 v100, v0
	v_mov_b32_e32 v101, v0
	v_mov_b32_e32 v102, v0
	v_mov_b32_e32 v103, v0
	v_mov_b32_e32 v112, v0
	v_mov_b32_e32 v113, v0
	v_mov_b32_e32 v114, v0
	v_mov_b32_e32 v115, v0
	v_mov_b32_e32 v116, v0
	v_mov_b32_e32 v117, v0
	v_mov_b32_e32 v118, v0
	v_mov_b32_e32 v119, v0
	v_mov_b32_e32 v72, v0
	v_mov_b32_e32 v73, v0
	v_mov_b32_e32 v74, v0
	v_mov_b32_e32 v75, v0
	v_mov_b32_e32 v76, v0
	v_mov_b32_e32 v77, v0
	v_mov_b32_e32 v78, v0
	v_mov_b32_e32 v79, v0
	v_mov_b32_e32 v88, v0
	v_mov_b32_e32 v89, v0
	v_mov_b32_e32 v90, v0
	v_mov_b32_e32 v91, v0
	v_mov_b32_e32 v92, v0
	v_mov_b32_e32 v93, v0
	v_mov_b32_e32 v94, v0
	v_mov_b32_e32 v95, v0
	v_mov_b32_e32 v104, v0
	v_mov_b32_e32 v105, v0
	v_mov_b32_e32 v106, v0
	v_mov_b32_e32 v107, v0
	v_mov_b32_e32 v108, v0
	v_mov_b32_e32 v109, v0
	v_mov_b32_e32 v110, v0
	v_mov_b32_e32 v111, v0
	v_mov_b32_e32 v120, v0
	v_mov_b32_e32 v121, v0
	v_mov_b32_e32 v122, v0
	v_mov_b32_e32 v123, v0
	v_mov_b32_e32 v124, v0
	v_mov_b32_e32 v125, v0
	v_mov_b32_e32 v126, v0
	v_mov_b32_e32 v127, v0
	v_lshl_add_u32 v138, s47, 8, v146
	v_ashrrev_i32_e32 v139, 31, v138
	v_lshl_add_u64 v[144:145], v[138:139], 2, s[12:13]
	global_load_dword v234, v[144:145], off
	global_load_dword v235, v[144:145], off offset:64
	global_load_dword v236, v[144:145], off offset:128
	global_load_dword v237, v[144:145], off offset:192
	global_load_dword v238, v[144:145], off offset:512
	global_load_dword v239, v[144:145], off offset:576
	global_load_dword v240, v[144:145], off offset:640
	global_load_dword v241, v[144:145], off offset:704

.LBB0_282:
	v_lshl_add_u32 v138, s47, 8, v146
	v_ashrrev_i32_e32 v139, 31, v138
	v_lshl_add_u64 v[144:145], v[138:139], 2, s[12:13]
	s_waitcnt vmcnt(8)
	v_lshl_or_b32 v142, s48, 8, v148
	v_mov_b64_e32 v[140:141], s[10:11]
	v_ashrrev_i32_e32 v143, 31, v142
	v_lshlrev_b64 v[142:143], 1, v[142:143]
	v_fmamk_f32 v139, v234, 0x3a800000, v166
	v_mul_f32_e32 v150, 0x4b800000, v139
	v_cmp_gt_f32_e32 vcc, s78, v139
	s_nop 1
	v_cndmask_b32_e32 v139, v139, v150, vcc
	v_rsq_f32_e32 v139, v139
	v_mad_i64_i32 v[150:151], s[6:7], v138, s79, v[140:141]
	v_lshl_add_u64 v[150:151], v[150:151], 0, v[142:143]
	v_mul_f32_e32 v152, 0x45800000, v139
	v_cndmask_b32_e32 v152, v139, v152, vcc
	v_pk_mul_f32 v[126:127], v[126:127], v[152:153] op_sel_hi:[1,0]
	v_pk_mul_f32 v[124:125], v[124:125], v[152:153] op_sel_hi:[1,0]
	v_pk_mul_f32 v[122:123], v[122:123], v[152:153] op_sel_hi:[1,0]
	v_pk_mul_f32 v[120:121], v[120:121], v[152:153] op_sel_hi:[1,0]
	v_pk_mul_f32 v[118:119], v[118:119], v[152:153] op_sel_hi:[1,0]
	v_pk_mul_f32 v[116:117], v[116:117], v[152:153] op_sel_hi:[1,0]
	v_pk_mul_f32 v[154:155], v[114:115], v[152:153] op_sel_hi:[1,0]
	v_pk_mul_f32 v[152:153], v[112:113], v[152:153] op_sel_hi:[1,0]
	v_cvt_pk_bf16_f32 v112, v124, v125
	v_cvt_pk_bf16_f32 v113, v126, v127
	v_cvt_pk_bf16_f32 v114, v120, v121
	v_cvt_pk_bf16_f32 v115, v122, v123
	v_cvt_pk_bf16_f32 v116, v116, v117
	v_cvt_pk_bf16_f32 v117, v118, v119
	v_cvt_pk_bf16_f32 v118, v152, v153
	v_cvt_pk_bf16_f32 v119, v154, v155
	global_store_dwordx4 v[150:151], v[112:115], off
	global_store_dwordx4 v[150:151], v[116:119], off offset:256
	s_nop 1
	v_or_b32_e32 v113, 16, v138
	v_fmamk_f32 v112, v235, 0x3a800000, v166
	v_mul_f32_e32 v114, 0x4b800000, v112
	v_cmp_gt_f32_e32 vcc, s78, v112
	s_nop 1
	v_cndmask_b32_e32 v112, v112, v114, vcc
	v_rsq_f32_e32 v114, v112
	v_mad_i64_i32 v[112:113], s[6:7], v113, s79, v[140:141]
	v_lshl_add_u64 v[112:113], v[112:113], 0, v[142:143]
	v_mul_f32_e32 v115, 0x45800000, v114
	v_cndmask_b32_e32 v114, v114, v115, vcc
	v_pk_mul_f32 v[110:111], v[110:111], v[114:115] op_sel_hi:[1,0]
	v_pk_mul_f32 v[108:109], v[108:109], v[114:115] op_sel_hi:[1,0]
	v_pk_mul_f32 v[106:107], v[106:107], v[114:115] op_sel_hi:[1,0]
	v_pk_mul_f32 v[104:105], v[104:105], v[114:115] op_sel_hi:[1,0]
	v_pk_mul_f32 v[102:103], v[102:103], v[114:115] op_sel_hi:[1,0]
	v_pk_mul_f32 v[100:101], v[100:101], v[114:115] op_sel_hi:[1,0]
	v_pk_mul_f32 v[116:117], v[98:99], v[114:115] op_sel_hi:[1,0]
	v_pk_mul_f32 v[114:115], v[96:97], v[114:115] op_sel_hi:[1,0]
	v_cvt_pk_bf16_f32 v96, v108, v109
	v_cvt_pk_bf16_f32 v97, v110, v111
	v_cvt_pk_bf16_f32 v98, v104, v105
	v_cvt_pk_bf16_f32 v99, v106, v107
	v_cvt_pk_bf16_f32 v100, v100, v101
	v_cvt_pk_bf16_f32 v101, v102, v103
	v_cvt_pk_bf16_f32 v102, v114, v115
	v_cvt_pk_bf16_f32 v103, v116, v117
	global_store_dwordx4 v[112:113], v[96:99], off
	global_store_dwordx4 v[112:113], v[100:103], off offset:256
	s_nop 1
	v_or_b32_e32 v97, 32, v138
	v_fmamk_f32 v96, v236, 0x3a800000, v166
	v_mul_f32_e32 v98, 0x4b800000, v96
	v_cmp_gt_f32_e32 vcc, s78, v96
	s_nop 1
	v_cndmask_b32_e32 v96, v96, v98, vcc
	v_rsq_f32_e32 v98, v96
	v_mad_i64_i32 v[96:97], s[6:7], v97, s79, v[140:141]
	v_lshl_add_u64 v[96:97], v[96:97], 0, v[142:143]
	v_mul_f32_e32 v99, 0x45800000, v98
	v_cndmask_b32_e32 v98, v98, v99, vcc
	v_pk_mul_f32 v[94:95], v[94:95], v[98:99] op_sel_hi:[1,0]
	v_pk_mul_f32 v[92:93], v[92:93], v[98:99] op_sel_hi:[1,0]
	v_pk_mul_f32 v[90:91], v[90:91], v[98:99] op_sel_hi:[1,0]
	v_pk_mul_f32 v[88:89], v[88:89], v[98:99] op_sel_hi:[1,0]
	v_pk_mul_f32 v[86:87], v[86:87], v[98:99] op_sel_hi:[1,0]
	v_pk_mul_f32 v[84:85], v[84:85], v[98:99] op_sel_hi:[1,0]
	v_pk_mul_f32 v[100:101], v[82:83], v[98:99] op_sel_hi:[1,0]
	v_pk_mul_f32 v[98:99], v[80:81], v[98:99] op_sel_hi:[1,0]
	v_cvt_pk_bf16_f32 v80, v92, v93
	v_cvt_pk_bf16_f32 v81, v94, v95
	v_cvt_pk_bf16_f32 v82, v88, v89
	v_cvt_pk_bf16_f32 v83, v90, v91
	v_cvt_pk_bf16_f32 v84, v84, v85
	v_cvt_pk_bf16_f32 v85, v86, v87
	v_cvt_pk_bf16_f32 v86, v98, v99
	v_cvt_pk_bf16_f32 v87, v100, v101
	global_store_dwordx4 v[96:97], v[80:83], off
	global_store_dwordx4 v[96:97], v[84:87], off offset:256
	s_nop 1
	v_or_b32_e32 v81, 48, v138
	v_fmamk_f32 v80, v237, 0x3a800000, v166
	v_mul_f32_e32 v82, 0x4b800000, v80
	v_cmp_gt_f32_e32 vcc, s78, v80
	s_nop 1
	v_cndmask_b32_e32 v80, v80, v82, vcc
	v_rsq_f32_e32 v82, v80
	v_mad_i64_i32 v[80:81], s[6:7], v81, s79, v[140:141]
	v_lshl_add_u64 v[80:81], v[80:81], 0, v[142:143]
	v_mul_f32_e32 v83, 0x45800000, v82
	v_cndmask_b32_e32 v82, v82, v83, vcc
	v_pk_mul_f32 v[78:79], v[78:79], v[82:83] op_sel_hi:[1,0]
	v_pk_mul_f32 v[76:77], v[76:77], v[82:83] op_sel_hi:[1,0]
	v_pk_mul_f32 v[74:75], v[74:75], v[82:83] op_sel_hi:[1,0]
	v_pk_mul_f32 v[72:73], v[72:73], v[82:83] op_sel_hi:[1,0]
	v_pk_mul_f32 v[70:71], v[70:71], v[82:83] op_sel_hi:[1,0]
	v_pk_mul_f32 v[68:69], v[68:69], v[82:83] op_sel_hi:[1,0]
	v_pk_mul_f32 v[84:85], v[66:67], v[82:83] op_sel_hi:[1,0]
	v_pk_mul_f32 v[82:83], v[64:65], v[82:83] op_sel_hi:[1,0]
	v_cvt_pk_bf16_f32 v64, v76, v77
	v_cvt_pk_bf16_f32 v65, v78, v79
	v_cvt_pk_bf16_f32 v66, v72, v73
	v_cvt_pk_bf16_f32 v67, v74, v75
	v_cvt_pk_bf16_f32 v68, v68, v69
	v_cvt_pk_bf16_f32 v69, v70, v71
	v_cvt_pk_bf16_f32 v70, v82, v83
	v_cvt_pk_bf16_f32 v71, v84, v85
	global_store_dwordx4 v[80:81], v[64:67], off
	global_store_dwordx4 v[80:81], v[68:71], off offset:256
	s_nop 1
	v_add_u32_e32 v65, 0x80, v138
	v_fmamk_f32 v64, v238, 0x3a800000, v166
	v_mul_f32_e32 v66, 0x4b800000, v64
	v_cmp_gt_f32_e32 vcc, s78, v64
	s_nop 1
	v_cndmask_b32_e32 v64, v64, v66, vcc
	v_rsq_f32_e32 v66, v64
	v_mad_i64_i32 v[64:65], s[6:7], v65, s79, v[140:141]
	v_lshl_add_u64 v[64:65], v[64:65], 0, v[142:143]
	v_mul_f32_e32 v67, 0x45800000, v66
	v_cndmask_b32_e32 v66, v66, v67, vcc
	v_pk_mul_f32 v[62:63], v[62:63], v[66:67] op_sel_hi:[1,0]
	v_pk_mul_f32 v[60:61], v[60:61], v[66:67] op_sel_hi:[1,0]
	v_pk_mul_f32 v[58:59], v[58:59], v[66:67] op_sel_hi:[1,0]
	v_pk_mul_f32 v[56:57], v[56:57], v[66:67] op_sel_hi:[1,0]
	v_pk_mul_f32 v[54:55], v[54:55], v[66:67] op_sel_hi:[1,0]
	v_pk_mul_f32 v[52:53], v[52:53], v[66:67] op_sel_hi:[1,0]
	v_pk_mul_f32 v[68:69], v[50:51], v[66:67] op_sel_hi:[1,0]
	v_pk_mul_f32 v[66:67], v[48:49], v[66:67] op_sel_hi:[1,0]
	v_cvt_pk_bf16_f32 v48, v60, v61
	v_cvt_pk_bf16_f32 v49, v62, v63
	v_cvt_pk_bf16_f32 v50, v56, v57
	v_cvt_pk_bf16_f32 v51, v58, v59
	v_cvt_pk_bf16_f32 v52, v52, v53
	v_cvt_pk_bf16_f32 v53, v54, v55
	v_cvt_pk_bf16_f32 v54, v66, v67
	v_cvt_pk_bf16_f32 v55, v68, v69
	global_store_dwordx4 v[64:65], v[48:51], off
	global_store_dwordx4 v[64:65], v[52:55], off offset:256
	s_nop 1
	v_add_u32_e32 v49, 0x90, v138
	v_fmamk_f32 v48, v239, 0x3a800000, v166
	v_mul_f32_e32 v50, 0x4b800000, v48
	v_cmp_gt_f32_e32 vcc, s78, v48
	s_nop 1
	v_cndmask_b32_e32 v48, v48, v50, vcc
	v_rsq_f32_e32 v50, v48
	v_mad_i64_i32 v[48:49], s[6:7], v49, s79, v[140:141]
	v_lshl_add_u64 v[48:49], v[48:49], 0, v[142:143]
	v_mul_f32_e32 v51, 0x45800000, v50
	v_cndmask_b32_e32 v50, v50, v51, vcc
	v_pk_mul_f32 v[46:47], v[46:47], v[50:51] op_sel_hi:[1,0]
	v_pk_mul_f32 v[44:45], v[44:45], v[50:51] op_sel_hi:[1,0]
	v_pk_mul_f32 v[42:43], v[42:43], v[50:51] op_sel_hi:[1,0]
	v_pk_mul_f32 v[40:41], v[40:41], v[50:51] op_sel_hi:[1,0]
	v_pk_mul_f32 v[38:39], v[38:39], v[50:51] op_sel_hi:[1,0]
	v_pk_mul_f32 v[36:37], v[36:37], v[50:51] op_sel_hi:[1,0]
	v_pk_mul_f32 v[52:53], v[34:35], v[50:51] op_sel_hi:[1,0]
	v_pk_mul_f32 v[50:51], v[32:33], v[50:51] op_sel_hi:[1,0]
	v_cvt_pk_bf16_f32 v32, v44, v45
	v_cvt_pk_bf16_f32 v33, v46, v47
	v_cvt_pk_bf16_f32 v34, v40, v41
	v_cvt_pk_bf16_f32 v35, v42, v43
	v_cvt_pk_bf16_f32 v36, v36, v37
	v_cvt_pk_bf16_f32 v37, v38, v39
	v_cvt_pk_bf16_f32 v38, v50, v51
	v_cvt_pk_bf16_f32 v39, v52, v53
	global_store_dwordx4 v[48:49], v[32:35], off
	global_store_dwordx4 v[48:49], v[36:39], off offset:256
	s_nop 1
	v_add_u32_e32 v33, 0xa0, v138
	v_fmamk_f32 v32, v240, 0x3a800000, v166
	v_mul_f32_e32 v34, 0x4b800000, v32
	v_cmp_gt_f32_e32 vcc, s78, v32
	s_nop 1
	v_cndmask_b32_e32 v32, v32, v34, vcc
	v_rsq_f32_e32 v34, v32
	v_mad_i64_i32 v[32:33], s[6:7], v33, s79, v[140:141]
	v_lshl_add_u64 v[32:33], v[32:33], 0, v[142:143]
	v_mul_f32_e32 v35, 0x45800000, v34
	v_cndmask_b32_e32 v34, v34, v35, vcc
	v_pk_mul_f32 v[30:31], v[30:31], v[34:35] op_sel_hi:[1,0]
	v_pk_mul_f32 v[28:29], v[28:29], v[34:35] op_sel_hi:[1,0]
	v_pk_mul_f32 v[26:27], v[26:27], v[34:35] op_sel_hi:[1,0]
	v_pk_mul_f32 v[24:25], v[24:25], v[34:35] op_sel_hi:[1,0]
	v_pk_mul_f32 v[22:23], v[22:23], v[34:35] op_sel_hi:[1,0]
	v_pk_mul_f32 v[20:21], v[20:21], v[34:35] op_sel_hi:[1,0]
	v_pk_mul_f32 v[36:37], v[18:19], v[34:35] op_sel_hi:[1,0]
	v_pk_mul_f32 v[34:35], v[16:17], v[34:35] op_sel_hi:[1,0]
	v_cvt_pk_bf16_f32 v16, v28, v29
	v_cvt_pk_bf16_f32 v17, v30, v31
	v_cvt_pk_bf16_f32 v18, v24, v25
	v_cvt_pk_bf16_f32 v19, v26, v27
	v_cvt_pk_bf16_f32 v20, v20, v21
	v_cvt_pk_bf16_f32 v21, v22, v23
	v_cvt_pk_bf16_f32 v22, v34, v35
	v_cvt_pk_bf16_f32 v23, v36, v37
	global_store_dwordx4 v[32:33], v[16:19], off
	global_store_dwordx4 v[32:33], v[20:23], off offset:256
	s_nop 1
	v_add_u32_e32 v17, 0xb0, v138
	s_andn2_b64 vcc, exec, s[4:5]
	s_mov_b64 s[4:5], -1
	v_fmamk_f32 v16, v241, 0x3a800000, v166
	v_mul_f32_e32 v18, 0x4b800000, v16
	v_cmp_gt_f32_e64 s[6:7], s78, v16
	s_nop 1
	v_cndmask_b32_e64 v16, v16, v18, s[6:7]
	v_rsq_f32_e32 v18, v16
	v_mad_i64_i32 v[16:17], s[26:27], v17, s79, v[140:141]
	v_lshl_add_u64 v[16:17], v[16:17], 0, v[142:143]
	v_mul_f32_e32 v19, 0x45800000, v18
	v_cndmask_b32_e64 v18, v18, v19, s[6:7]
	v_pk_mul_f32 v[14:15], v[14:15], v[18:19] op_sel_hi:[1,0]
	v_pk_mul_f32 v[12:13], v[12:13], v[18:19] op_sel_hi:[1,0]
	v_pk_mul_f32 v[10:11], v[10:11], v[18:19] op_sel_hi:[1,0]
	v_pk_mul_f32 v[8:9], v[8:9], v[18:19] op_sel_hi:[1,0]
	v_pk_mul_f32 v[6:7], v[6:7], v[18:19] op_sel_hi:[1,0]
	v_pk_mul_f32 v[4:5], v[4:5], v[18:19] op_sel_hi:[1,0]
	v_pk_mul_f32 v[20:21], v[2:3], v[18:19] op_sel_hi:[1,0]
	v_pk_mul_f32 v[18:19], v[0:1], v[18:19] op_sel_hi:[1,0]
	v_cvt_pk_bf16_f32 v0, v12, v13
	v_cvt_pk_bf16_f32 v1, v14, v15
	v_cvt_pk_bf16_f32 v2, v8, v9
	v_cvt_pk_bf16_f32 v3, v10, v11
	v_cvt_pk_bf16_f32 v4, v4, v5
	v_cvt_pk_bf16_f32 v5, v6, v7
	v_cvt_pk_bf16_f32 v6, v18, v19
	v_cvt_pk_bf16_f32 v7, v20, v21
	global_store_dwordx4 v[16:17], v[0:3], off
	global_store_dwordx4 v[16:17], v[4:7], off offset:256
	s_cbranch_vccnz .LBB0_275
	s_andn2_b64 vcc, exec, s[8:9]
	s_cbranch_vccnz .LBB0_274
	s_barrier
	s_branch .LBB0_274

.LBB0_503:
	s_mov_b32 s2, 0x78787879
	v_add_u32_e32 v2, 0x200, v1
	s_movk_i32 s8, 0xabf
	v_mul_hi_i32 v3, v1, s2
	v_cmp_lt_i32_e32 vcc, s8, v1
	v_mov_b32_e32 v1, v2
	v_lshrrev_b32_e32 v2, 31, v3
	v_ashrrev_i32_e32 v3, 9, v3
	v_add_u32_e32 v2, v3, v2
	v_add_u32_e32 v8, 1, v2
	v_mul_i32_i24_e32 v2, 0x440, v2
	v_lshlrev_b32_e32 v2, 4, v2
	v_mul_i32_i24_e32 v3, 0x4440, v8
	v_sub_u32_e32 v6, v0, v2
	v_sub_u32_e32 v11, v3, v2
	ds_read_b128 v[2:5], v6
	ds_read_b64 v[6:7], v6 offset:16
	s_or_b64 s[6:7], vcc, s[6:7]
	v_cmp_gt_u32_e32 vcc, 2, v8
	v_lshlrev_b32_e32 v9, 4, v8
	v_add_u32_e32 v11, v0, v11
	s_waitcnt lgkmcnt(1)
	v_cndmask_b32_e32 v2, v3, v2, vcc
	v_cndmask_b32_e32 v3, v4, v3, vcc
	v_cndmask_b32_e32 v4, v5, v4, vcc
	s_waitcnt lgkmcnt(0)
	v_cndmask_b32_e32 v5, v6, v5, vcc
	v_cndmask_b32_e32 v6, v7, v6, vcc
	v_add_u32_e32 v0, 0x2000, v0
	v_alignbit_b32 v2, v3, v2, v9
	v_alignbit_b32 v3, v4, v3, v9
	v_alignbit_b32 v4, v5, v4, v9
	v_alignbit_b32 v5, v6, v5, v9
	ds_write_b128 v11, v[2:5]
	s_andn2_b64 exec, exec, s[6:7]
	s_cbranch_execnz .LBB0_503
.LBB0_504:
	s_or_b64 exec, exec, s[4:5]
	v_sub_u32_e32 v2, 0, v10
	v_bfe_u32 v136, v10, 5, 1
	v_and_b32_e32 v0, 31, v10
	s_ashr_i32 s4, s1, 4
	v_and_b32_e32 v2, 3, v2
	s_and_b32 s1, s4, -4
	v_lshlrev_b32_e32 v139, 4, v136
	v_add_lshl_u32 v0, v2, v0, 1
	s_sub_i32 s7, s1, 31
	v_mul_u32_u24_e32 v3, 0x4440, v2
	s_add_i32 s2, 0, 0x11400
	v_sub_u32_e32 v2, v139, v0
	v_add3_u32 v2, s2, v3, v2
	s_lshl_b32 s2, s7, 8
	v_subrev_u32_e32 v2, s2, v2
	v_add_u32_e32 v4, 0x2140, v2
	s_waitcnt lgkmcnt(0)
	s_barrier
	v_add_u32_e32 v5, 0x2160, v2
	ds_read2_b64 v[108:111], v4 offset1:1
	ds_read2_b64 v[96:99], v5 offset1:1
	v_add_u32_e32 v4, 0x2180, v2
	v_add_u32_e32 v5, 0x21a0, v2
	ds_read2_b64 v[104:107], v4 offset1:1
	ds_read2_b64 v[92:95], v5 offset1:1
	v_add_u32_e32 v4, 0x21c0, v2
	v_add_u32_e32 v5, 0x21e0, v2
	ds_read2_b64 v[100:103], v4 offset1:1
	ds_read2_b64 v[84:87], v5 offset1:1
	v_add_u32_e32 v4, 0x2200, v2
	v_add_u32_e32 v5, 0x2220, v2
	ds_read2_b64 v[116:119], v4 offset1:1
	ds_read2_b64 v[112:115], v5 offset1:1
	v_add_u32_e32 v4, 0x2240, v2
	v_add_u32_e32 v5, 0x2260, v2
	ds_read2_b64 v[88:91], v4 offset1:1
	ds_read2_b64 v[76:79], v5 offset1:1
	v_add_u32_e32 v4, 0x2280, v2
	v_add_u32_e32 v5, 0x22a0, v2
	ds_read2_b64 v[80:83], v4 offset1:1
	ds_read2_b64 v[68:71], v5 offset1:1
	v_add_u32_e32 v4, 0x22c0, v2
	v_add_u32_e32 v2, 0x22e0, v2
	ds_read2_b64 v[72:75], v4 offset1:1
	ds_read2_b64 v[64:67], v2 offset1:1
	s_or_b32 s2, s4, 3
	s_lshl_b32 s4, s4, 8
	v_and_b32_e32 v137, 3, v10
	v_bfe_u32 v138, v10, 2, 3
	v_sub_u32_e32 v0, v3, v0
	s_and_b32 s4, s4, 0xfffffc00
	v_mul_u32_u24_e32 v1, 0x2240, v138
	s_add_i32 s5, 0, 0x11200
	v_mul_u32_u24_e32 v2, 0x110, v137
	v_subrev_u32_e32 v0, s4, v0
	v_mov_b32_e32 v48, 0
	v_add_u32_e32 v140, s5, v139
	v_add3_u32 v141, v1, v2, 0
	v_add_u32_e32 v142, 29, v137
	v_add_u32_e32 v143, 0, v0
	v_mov_b32_e32 v49, v48
	v_mov_b32_e32 v50, v48
	v_mov_b32_e32 v51, v48
	v_mov_b32_e32 v52, v48
	v_mov_b32_e32 v53, v48
	v_mov_b32_e32 v54, v48
	v_mov_b32_e32 v55, v48
	v_mov_b32_e32 v56, v48
	v_mov_b32_e32 v57, v48
	v_mov_b32_e32 v58, v48
	v_mov_b32_e32 v59, v48
	v_mov_b32_e32 v60, v48
	v_mov_b32_e32 v61, v48
	v_mov_b32_e32 v62, v48
	v_mov_b32_e32 v63, v48
	v_mov_b32_e32 v32, v48
	v_mov_b32_e32 v33, v48
	v_mov_b32_e32 v34, v48
	v_mov_b32_e32 v35, v48
	v_mov_b32_e32 v36, v48
	v_mov_b32_e32 v37, v48
	v_mov_b32_e32 v38, v48
	v_mov_b32_e32 v39, v48
	v_mov_b32_e32 v40, v48
	v_mov_b32_e32 v41, v48
	v_mov_b32_e32 v42, v48
	v_mov_b32_e32 v43, v48
	v_mov_b32_e32 v44, v48
	v_mov_b32_e32 v45, v48
	v_mov_b32_e32 v46, v48
	v_mov_b32_e32 v47, v48
	v_mov_b32_e32 v16, v48
	v_mov_b32_e32 v17, v48
	v_mov_b32_e32 v18, v48
	v_mov_b32_e32 v19, v48
	v_mov_b32_e32 v20, v48
	v_mov_b32_e32 v21, v48
	v_mov_b32_e32 v22, v48
	v_mov_b32_e32 v23, v48
	v_mov_b32_e32 v24, v48
	v_mov_b32_e32 v25, v48
	v_mov_b32_e32 v26, v48
	v_mov_b32_e32 v27, v48
	v_mov_b32_e32 v28, v48
	v_mov_b32_e32 v29, v48
	v_mov_b32_e32 v30, v48
	v_mov_b32_e32 v31, v48
	v_mov_b32_e32 v0, v48
	v_mov_b32_e32 v1, v48
	v_mov_b32_e32 v2, v48
	v_mov_b32_e32 v3, v48
	v_mov_b32_e32 v4, v48
	v_mov_b32_e32 v5, v48
	v_mov_b32_e32 v6, v48
	v_mov_b32_e32 v7, v48
	v_mov_b32_e32 v8, v48
	v_mov_b32_e32 v9, v48
	v_mov_b32_e32 v10, v48
	v_mov_b32_e32 v11, v48
	v_mov_b32_e32 v12, v48
	v_mov_b32_e32 v13, v48
	v_mov_b32_e32 v14, v48
	v_mov_b32_e32 v15, v48
	s_branch .LBB0_506

.LBB0_713:
	s_cmpk_lt_i32 s2, 0x72
	s_cbranch_scc1 .Lstag8_done
	s_sub_i32 s98, s2, 0x72
	s_mul_i32 s98, s98, 6

	.amdhsa_kernel _Z4mega6Params
		.amdhsa_group_segment_fixed_size 0
		.amdhsa_private_segment_fixed_size 0
		.amdhsa_kernarg_size 480
		.amdhsa_user_sgpr_count 2
		.amdhsa_user_sgpr_dispatch_ptr 0
		.amdhsa_user_sgpr_queue_ptr 0
		.amdhsa_user_sgpr_kernarg_segment_ptr 1
		.amdhsa_user_sgpr_dispatch_id 0
		.amdhsa_user_sgpr_kernarg_preload_length 0
		.amdhsa_user_sgpr_kernarg_preload_offset 0
		.amdhsa_user_sgpr_private_segment_size 0
		.amdhsa_uses_dynamic_stack 0
		.amdhsa_enable_private_segment 0
		.amdhsa_system_sgpr_workgroup_id_x 1
		.amdhsa_system_sgpr_workgroup_id_y 0
		.amdhsa_system_sgpr_workgroup_id_z 0
		.amdhsa_system_sgpr_workgroup_info 0
		.amdhsa_system_vgpr_workitem_id 2
		.amdhsa_next_free_vgpr 243
		.amdhsa_next_free_sgpr 100
		.amdhsa_accum_offset 244
		.amdhsa_reserve_vcc 1
		.amdhsa_float_round_mode_32 0
		.amdhsa_float_round_mode_16_64 0
		.amdhsa_float_denorm_mode_32 3
		.amdhsa_float_denorm_mode_16_64 3
		.amdhsa_dx10_clamp 1
		.amdhsa_ieee_mode 1
		.amdhsa_fp16_overflow 0
		.amdhsa_tg_split 0
		.amdhsa_exception_fp_ieee_invalid_op 0
		.amdhsa_exception_fp_denorm_src 0
		.amdhsa_exception_fp_ieee_div_zero 0
		.amdhsa_exception_fp_ieee_overflow 0
		.amdhsa_exception_fp_ieee_underflow 0
		.amdhsa_exception_fp_ieee_inexact 0
		.amdhsa_exception_int_div_zero 0
	.end_amdhsa_kernel

.Lfunc_end0:
	.size	_Z4mega6Params, .Lfunc_end0-_Z4mega6Params
	.set _Z4mega6Params.num_vgpr, 243
	.set _Z4mega6Params.num_agpr, 0
	.set _Z4mega6Params.numbered_sgpr, 100
	.set _Z4mega6Params.num_named_barrier, 0
	.set _Z4mega6Params.private_seg_size, 0
	.set _Z4mega6Params.uses_vcc, 1
	.set _Z4mega6Params.uses_flat_scratch, 0
	.set _Z4mega6Params.has_dyn_sized_stack, 0
	.set _Z4mega6Params.has_recursion, 0
	.set _Z4mega6Params.has_indirect_call, 0

amdhsa.kernels:
  - .agpr_count:     0
    .args:
      - .offset:         0
        .size:           224
        .value_kind:     by_value
      - .offset:         224
        .size:           4
        .value_kind:     hidden_block_count_x
      - .offset:         228
        .size:           4
        .value_kind:     hidden_block_count_y
      - .offset:         232
        .size:           4
        .value_kind:     hidden_block_count_z
      - .offset:         236
        .size:           2
        .value_kind:     hidden_group_size_x
      - .offset:         238
        .size:           2
        .value_kind:     hidden_group_size_y
      - .offset:         240
        .size:           2
        .value_kind:     hidden_group_size_z
      - .offset:         242
        .size:           2
        .value_kind:     hidden_remainder_x
      - .offset:         244
        .size:           2
        .value_kind:     hidden_remainder_y
      - .offset:         246
        .size:           2
        .value_kind:     hidden_remainder_z
      - .offset:         264
        .size:           8
        .value_kind:     hidden_global_offset_x
      - .offset:         272
        .size:           8
        .value_kind:     hidden_global_offset_y
      - .offset:         280
        .size:           8
        .value_kind:     hidden_global_offset_z
      - .offset:         288
        .size:           2
        .value_kind:     hidden_grid_dims
      - .offset:         312
        .size:           8
        .value_kind:     hidden_multigrid_sync_arg
      - .offset:         344
        .size:           4
        .value_kind:     hidden_dynamic_lds_size
    .group_segment_fixed_size: 0
    .kernarg_segment_align: 8
    .kernarg_segment_size: 480
    .language:       OpenCL C
    .language_version:
      - 2
      - 0
    .max_flat_workgroup_size: 512
    .name:           _Z4mega6Params
    .private_segment_fixed_size: 0
    .sgpr_count:     106
    .sgpr_spill_count: 37
    .symbol:         _Z4mega6Params.kd
    .uniform_work_group_size: 1
    .uses_dynamic_stack: false
    .vgpr_count:     243
    .vgpr_spill_count: 0
    .wavefront_size: 64
